# prep phase: gate-column GEMM issues four k-steps of loads together; compression MLP loops keep loads in flight
# speedup vs baseline: 1.1406x; 1.0047x over previous
; #define MFMA32(a, b, c) __builtin_amdgcn_mfma_f32_32x32x16_bf16((a), (b), (c), 0, 0, 0)
; DI unsigned f2bf(float f) { unsigned u = __builtin_bit_cast(unsigned, f); return (u + 0x7fffu + ((u >> 16) & 1u)) >> 16; }
; DI int crow(int r, int hi) { return (r & 3) + 8 * (r >> 2) + 4 * hi; }
; DI void phase_prep(const Args& a, int layer, LAS unsigned char* lds) {
;     ...
;         for (int it = NGW - 1 - gw; it < M / 32; it += NGW) {
;             const bf16_t* ar = XN + (size_t)(it * 32 + c) * D + hi * 8;
;             const bf16_t* b0 = wg + (size_t)c * D + hi * 8, *b1 = wg + (size_t)(32 + c) * D + hi * 8;
;             f32x16 a0, a1;
; #pragma unroll
;             for (int r = 0; r < 16; ++r) { a0[r] = 0.f; a1[r] = 0.f; }
; #pragma unroll 8
;             for (int kk = 0; kk < 128; ++kk) {
;                 const bf16x8 af = *(const bf16x8*)(ar + kk * 16);
;                 a0 = MFMA32(af, *(const bf16x8*)(b0 + kk * 16), a0);
;                 a1 = MFMA32(af, *(const bf16x8*)(b1 + kk * 16), a1);
;             }
; #pragma unroll
;             for (int r = 0; r < 16; ++r) {
;                 bf16_t* pr = Pw + (size_t)(it * 32 + crow(r, hi)) * NP + C_GATE;
;                 pr[c] = (bf16_t)f2bf(a0[r]);
;                 if (c < 16) pr[32 + c] = (bf16_t)f2bf(a1[r]);
;             }
.LBB0_357:
	s_waitcnt vmcnt(0)
	s_mov_b32 s38, 0x18000000
	s_mov_b32 s39, 0
	v_lshl_add_u64 v[110:111], v[40:41], 0, s[38:39]
	s_mov_b32 s38, 0xc00000
	v_lshl_add_u64 v[112:113], v[38:39], 0, s[38:39]
	s_mov_b32 s38, 0xc20000
	v_lshl_add_u64 v[114:115], v[38:39], 0, s[38:39]
	s_mov_b64 s[38:39], 0x100
	s_mov_b32 s8, 0
.Lp_gg_loop:
	global_load_dwordx4 v[50:53], v[110:111], off
	global_load_dwordx4 v[54:57], v[110:111], off offset:32
	global_load_dwordx4 v[58:61], v[110:111], off offset:64
	global_load_dwordx4 v[62:65], v[110:111], off offset:96
	global_load_dwordx4 v[66:69], v[112:113], off
	global_load_dwordx4 v[70:73], v[112:113], off offset:32
	global_load_dwordx4 v[74:77], v[112:113], off offset:64
	global_load_dwordx4 v[78:81], v[112:113], off offset:96
	global_load_dwordx4 v[82:85], v[114:115], off
	global_load_dwordx4 v[86:89], v[114:115], off offset:32
	global_load_dwordx4 v[90:93], v[114:115], off offset:64
	global_load_dwordx4 v[94:97], v[114:115], off offset:96
	s_waitcnt vmcnt(0)
	v_mfma_f32_32x32x16_bf16 v[0:15], v[50:53], v[66:69], v[0:15]
	v_mfma_f32_32x32x16_bf16 v[16:31], v[50:53], v[82:85], v[16:31]
	v_mfma_f32_32x32x16_bf16 v[0:15], v[54:57], v[70:73], v[0:15]
	v_mfma_f32_32x32x16_bf16 v[16:31], v[54:57], v[86:89], v[16:31]
	v_mfma_f32_32x32x16_bf16 v[0:15], v[58:61], v[74:77], v[0:15]
	v_mfma_f32_32x32x16_bf16 v[16:31], v[58:61], v[90:93], v[16:31]
	v_mfma_f32_32x32x16_bf16 v[0:15], v[62:65], v[78:81], v[0:15]
	v_mfma_f32_32x32x16_bf16 v[16:31], v[62:65], v[94:97], v[16:31]
	global_load_dwordx4 v[50:53], v[110:111], off offset:128
	global_load_dwordx4 v[54:57], v[110:111], off offset:160
	global_load_dwordx4 v[58:61], v[110:111], off offset:192
	global_load_dwordx4 v[62:65], v[110:111], off offset:224
	global_load_dwordx4 v[66:69], v[112:113], off offset:128
	global_load_dwordx4 v[70:73], v[112:113], off offset:160
	global_load_dwordx4 v[74:77], v[112:113], off offset:192
	global_load_dwordx4 v[78:81], v[112:113], off offset:224
	global_load_dwordx4 v[82:85], v[114:115], off offset:128
	global_load_dwordx4 v[86:89], v[114:115], off offset:160
	global_load_dwordx4 v[90:93], v[114:115], off offset:192
	global_load_dwordx4 v[94:97], v[114:115], off offset:224
	s_waitcnt vmcnt(0)
	v_mfma_f32_32x32x16_bf16 v[0:15], v[50:53], v[66:69], v[0:15]
	v_mfma_f32_32x32x16_bf16 v[16:31], v[50:53], v[82:85], v[16:31]
	v_mfma_f32_32x32x16_bf16 v[0:15], v[54:57], v[70:73], v[0:15]
	v_mfma_f32_32x32x16_bf16 v[16:31], v[54:57], v[86:89], v[16:31]
	v_mfma_f32_32x32x16_bf16 v[0:15], v[58:61], v[74:77], v[0:15]
	v_mfma_f32_32x32x16_bf16 v[16:31], v[58:61], v[90:93], v[16:31]
	v_mfma_f32_32x32x16_bf16 v[0:15], v[62:65], v[78:81], v[0:15]
	v_mfma_f32_32x32x16_bf16 v[16:31], v[62:65], v[94:97], v[16:31]
	v_lshl_add_u64 v[110:111], v[110:111], 0, s[38:39]
	v_lshl_add_u64 v[112:113], v[112:113], 0, s[38:39]
	v_lshl_add_u64 v[114:115], v[114:115], 0, s[38:39]
	s_add_u32 s8, s8, 1
	s_cmp_lt_u32 s8, 16
	s_cbranch_scc1 .Lp_gg_loop
	v_lshl_or_b32 v37, v46, 5, v48
	v_mov_b64_e32 v[40:41], s[30:31]
	v_mad_i64_i32 v[40:41], s[0:1], v37, s74, v[40:41]
	s_mov_b64 s[0:1], 0x1800
	s_nop 0
	v_lshl_add_u64 v[40:41], v[40:41], 0, s[0:1]
	s_nop 1
	v_bfe_u32 v49, v0, 16, 1
	v_add3_u32 v0, v0, v49, s28
	v_lshl_add_u64 v[50:51], v[128:129], 1, v[40:41]
	global_store_short_d16_hi v[50:51], v0, off
	s_and_saveexec_b64 s[0:1], vcc
	s_cbranch_execz .LBB0_360
	v_bfe_u32 v0, v16, 16, 1
	v_add3_u32 v0, v16, v0, s28
	v_lshl_add_u64 v[40:41], v[32:33], 1, v[40:41]
	global_store_short_d16_hi v[40:41], v0, off

; #define MFMA32(a, b, c) __builtin_amdgcn_mfma_f32_32x32x16_bf16((a), (b), (c), 0, 0, 0)
; DI void phase_prep(const Args& a, int layer, LAS unsigned char* lds) {
;     ...
; #pragma unroll 4
;             for (int kk = 0; kk < 128; ++kk) {
;                 const int tok = kk >> 2, d = (kk & 3) * 16 + hi * 8;
;                 const u32x4 sv = *(const u32x4*)(src + (size_t)tok * NP + d);
;                 const f32x4 p0 = *(const f32x4*)(pos + tok * 64 + d), p1 = *(const f32x4*)(pos + tok * 64 + d + 4);
;                 const bf16x8 af = pack8(bflo(sv.x) + p0.x, bfhi(sv.x) + p0.y, bflo(sv.y) + p0.z, bfhi(sv.y) + p0.w,
;                                         bflo(sv.z) + p1.x, bfhi(sv.z) + p1.y, bflo(sv.w) + p1.z, bfhi(sv.w) + p1.w);
;                 const bf16x8 bf = *(const bf16x8*)(bsrc + kk * 16);
;                 acc = MFMA32(af, bf, acc);
;             }
.LBB0_395:
	s_waitcnt vmcnt(0)
	s_mov_b32 s47, 0
	s_mov_b32 s46, 0
	s_mov_b32 s17, 0
	s_mov_b32 s23, 0
	s_mov_b32 s8, 0
	v_lshl_add_u64 v[124:125], v[36:37], 0, s[46:47]
	global_load_dwordx4 v[48:51], v[38:39], off offset:-64
	global_load_dwordx4 v[52:55], v[124:125], off
	global_load_dwordx4 v[56:59], v[124:125], off offset:16
	global_load_dwordx4 v[60:63], v[40:41], off offset:-64
	global_load_dwordx4 v[64:67], v[38:39], off offset:-32
	global_load_dwordx4 v[68:71], v[124:125], off offset:64
	global_load_dwordx4 v[72:75], v[124:125], off offset:80
	global_load_dwordx4 v[76:79], v[40:41], off offset:-32
	global_load_dwordx4 v[80:83], v[38:39], off offset:0
	global_load_dwordx4 v[84:87], v[124:125], off offset:128
	global_load_dwordx4 v[88:91], v[124:125], off offset:144
	global_load_dwordx4 v[92:95], v[40:41], off offset:0
	global_load_dwordx4 v[96:99], v[38:39], off offset:32
	global_load_dwordx4 v[100:103], v[124:125], off offset:192
	global_load_dwordx4 v[104:107], v[124:125], off offset:208
	global_load_dwordx4 v[108:111], v[40:41], off offset:32
.Lp_c1_loop:
	s_cmp_eq_u32 s8, 31
	s_cselect_b32 s16, 0, 0x1a00
	s_cselect_b32 s22, 0, 0x80
	s_cselect_b32 s9, 0, 0x100
	s_add_u32 s46, s46, s9
	v_lshl_add_u64 v[118:119], v[38:39], 0, s[16:17]
	v_lshl_add_u64 v[120:121], v[40:41], 0, s[22:23]
	v_lshl_add_u64 v[124:125], v[36:37], 0, s[46:47]
	s_waitcnt vmcnt(12)
	v_lshlrev_b32_e32 v16, 16, v48
	v_and_b32_e32 v17, 0xffff0000, v48
	v_lshlrev_b32_e32 v18, 16, v49
	v_and_b32_e32 v19, 0xffff0000, v49
	v_lshlrev_b32_e32 v20, 16, v50
	v_and_b32_e32 v21, 0xffff0000, v50
	v_lshlrev_b32_e32 v22, 16, v51
	v_and_b32_e32 v23, 0xffff0000, v51
	v_pk_add_f32 v[16:17], v[52:53], v[16:17]
	v_pk_add_f32 v[18:19], v[54:55], v[18:19]
	v_pk_add_f32 v[20:21], v[56:57], v[20:21]
	v_pk_add_f32 v[22:23], v[58:59], v[22:23]
	v_cvt_pk_bf16_f32 v112, v16, v17
	v_cvt_pk_bf16_f32 v113, v18, v19
	v_cvt_pk_bf16_f32 v114, v20, v21
	v_cvt_pk_bf16_f32 v115, v22, v23
	s_nop 1
	v_mfma_f32_32x32x16_bf16 v[0:15], v[112:115], v[60:63], v[0:15]
	global_load_dwordx4 v[48:51], v[118:119], off offset:-64
	global_load_dwordx4 v[52:55], v[124:125], off
	global_load_dwordx4 v[56:59], v[124:125], off offset:16
	global_load_dwordx4 v[60:63], v[120:121], off offset:-64
	s_waitcnt vmcnt(12)
	v_lshlrev_b32_e32 v16, 16, v64
	v_and_b32_e32 v17, 0xffff0000, v64
	v_lshlrev_b32_e32 v18, 16, v65
	v_and_b32_e32 v19, 0xffff0000, v65
	v_lshlrev_b32_e32 v20, 16, v66
	v_and_b32_e32 v21, 0xffff0000, v66
	v_lshlrev_b32_e32 v22, 16, v67
	v_and_b32_e32 v23, 0xffff0000, v67
	v_pk_add_f32 v[16:17], v[68:69], v[16:17]
	v_pk_add_f32 v[18:19], v[70:71], v[18:19]
	v_pk_add_f32 v[20:21], v[72:73], v[20:21]
	v_pk_add_f32 v[22:23], v[74:75], v[22:23]
	v_cvt_pk_bf16_f32 v112, v16, v17
	v_cvt_pk_bf16_f32 v113, v18, v19
	v_cvt_pk_bf16_f32 v114, v20, v21
	v_cvt_pk_bf16_f32 v115, v22, v23
	s_nop 1
	v_mfma_f32_32x32x16_bf16 v[0:15], v[112:115], v[76:79], v[0:15]
	global_load_dwordx4 v[64:67], v[118:119], off offset:-32
	global_load_dwordx4 v[68:71], v[124:125], off offset:64
	global_load_dwordx4 v[72:75], v[124:125], off offset:80
	global_load_dwordx4 v[76:79], v[120:121], off offset:-32
	s_waitcnt vmcnt(12)
	v_lshlrev_b32_e32 v16, 16, v80
	v_and_b32_e32 v17, 0xffff0000, v80
	v_lshlrev_b32_e32 v18, 16, v81
	v_and_b32_e32 v19, 0xffff0000, v81
	v_lshlrev_b32_e32 v20, 16, v82
	v_and_b32_e32 v21, 0xffff0000, v82
	v_lshlrev_b32_e32 v22, 16, v83
	v_and_b32_e32 v23, 0xffff0000, v83
	v_pk_add_f32 v[16:17], v[84:85], v[16:17]
	v_pk_add_f32 v[18:19], v[86:87], v[18:19]
	v_pk_add_f32 v[20:21], v[88:89], v[20:21]
	v_pk_add_f32 v[22:23], v[90:91], v[22:23]
	v_cvt_pk_bf16_f32 v112, v16, v17
	v_cvt_pk_bf16_f32 v113, v18, v19
	v_cvt_pk_bf16_f32 v114, v20, v21
	v_cvt_pk_bf16_f32 v115, v22, v23
	s_nop 1
	v_mfma_f32_32x32x16_bf16 v[0:15], v[112:115], v[92:95], v[0:15]
	global_load_dwordx4 v[80:83], v[118:119], off offset:0
	global_load_dwordx4 v[84:87], v[124:125], off offset:128
	global_load_dwordx4 v[88:91], v[124:125], off offset:144
	global_load_dwordx4 v[92:95], v[120:121], off offset:0
	s_waitcnt vmcnt(12)
	v_lshlrev_b32_e32 v16, 16, v96
	v_and_b32_e32 v17, 0xffff0000, v96
	v_lshlrev_b32_e32 v18, 16, v97
	v_and_b32_e32 v19, 0xffff0000, v97
	v_lshlrev_b32_e32 v20, 16, v98
	v_and_b32_e32 v21, 0xffff0000, v98
	v_lshlrev_b32_e32 v22, 16, v99
	v_and_b32_e32 v23, 0xffff0000, v99
	v_pk_add_f32 v[16:17], v[100:101], v[16:17]
	v_pk_add_f32 v[18:19], v[102:103], v[18:19]
	v_pk_add_f32 v[20:21], v[104:105], v[20:21]
	v_pk_add_f32 v[22:23], v[106:107], v[22:23]
	v_cvt_pk_bf16_f32 v112, v16, v17
	v_cvt_pk_bf16_f32 v113, v18, v19
	v_cvt_pk_bf16_f32 v114, v20, v21
	v_cvt_pk_bf16_f32 v115, v22, v23
	s_nop 1
	v_mfma_f32_32x32x16_bf16 v[0:15], v[112:115], v[108:111], v[0:15]
	global_load_dwordx4 v[96:99], v[118:119], off offset:32
	global_load_dwordx4 v[100:103], v[124:125], off offset:192
	global_load_dwordx4 v[104:107], v[124:125], off offset:208
	global_load_dwordx4 v[108:111], v[120:121], off offset:32
	v_mov_b64_e32 v[38:39], v[118:119]
	v_mov_b64_e32 v[40:41], v[120:121]
	s_add_u32 s8, s8, 1
	s_cmp_lt_u32 s8, 32
	s_cbranch_scc1 .Lp_c1_loop
; DI int crow(int r, int hi) { return (r & 3) + 8 * (r >> 2) + 4 * hi; }
; DI float gelu_tanh(float x) {
;     const float y = 0.7978845608028654f * (x + 0.044715f * x * x * x);
;     const float t = __expf(2.f * y);
;     const float th = 1.f - 2.f / (t + 1.f);
;     return 0.5f * x * (1.f + th);
; }
; DI void phase_prep(const Args& a, int layer, LAS unsigned char* lds) {
;     ...
; #pragma unroll
;             for (int r = 0; r < 16; ++r) H[(rg * 32 + crow(r, hi)) * 129 + nt * 32 + c] = gelu_tanh(acc[r]);
	s_waitcnt vmcnt(0)
	s_nop 10
	v_mul_f32_e32 v16, 0x3d372713, v0
	v_mul_f32_e32 v16, v0, v16
	v_fma_f32 v16, v0, v16, v0
	v_mul_f32_e32 v16, 0x3f4c422a, v16
	v_add_f32_e32 v16, v16, v16
	v_mul_f32_e32 v16, 0x3fb8aa3b, v16
	v_exp_f32_e32 v16, v16
	v_mul_f32_e32 v0, 0.5, v0
	s_and_b64 s[8:9], s[44:45], exec
	s_cselect_b32 s9, s86, s64
	v_add_f32_e32 v16, 1.0, v16
	v_div_scale_f32 v17, s[22:23], v16, v16, 2.0
	v_rcp_f32_e32 v18, v17
	v_div_scale_f32 v19, vcc, 2.0, v16, 2.0
	s_cselect_b32 s8, s87, s65
	v_fma_f32 v20, -v17, v18, 1.0
	v_fmac_f32_e32 v18, v20, v18
	v_mul_f32_e32 v20, v19, v18
	v_fma_f32 v21, -v17, v20, v19
	v_fmac_f32_e32 v20, v21, v18
	v_fma_f32 v17, -v17, v20, v19
	v_mul_f32_e32 v19, 0x3d372713, v1
	v_mul_f32_e32 v19, v1, v19
	v_fma_f32 v19, v1, v19, v1
	v_mul_f32_e32 v19, 0x3f4c422a, v19
	v_add_f32_e32 v19, v19, v19
	v_mul_f32_e32 v19, 0x3fb8aa3b, v19
	v_exp_f32_e32 v19, v19
	v_div_fmas_f32 v17, v17, v18, v20
	v_div_fixup_f32 v16, v17, v16, 2.0
	v_sub_f32_e32 v16, 1.0, v16
	v_add_f32_e32 v17, 1.0, v19
	v_div_scale_f32 v18, s[22:23], v17, v17, 2.0
	v_rcp_f32_e32 v19, v18
	v_add_f32_e32 v16, 1.0, v16
	v_mul_f32_e32 v0, v0, v16
	v_mul_f32_e32 v1, 0.5, v1
	v_fma_f32 v16, -v18, v19, 1.0
	v_fmac_f32_e32 v19, v16, v19
	v_div_scale_f32 v16, vcc, 2.0, v17, 2.0
	v_mul_f32_e32 v20, v16, v19
	v_fma_f32 v21, -v18, v20, v16
	v_fmac_f32_e32 v20, v21, v19
	v_fma_f32 v16, -v18, v20, v16
	v_mul_f32_e32 v18, 0x3d372713, v2
	v_mul_f32_e32 v18, v2, v18
	v_fma_f32 v18, v2, v18, v2
	v_mul_f32_e32 v18, 0x3f4c422a, v18
	v_add_f32_e32 v18, v18, v18
	v_mul_f32_e32 v18, 0x3fb8aa3b, v18
	v_exp_f32_e32 v18, v18
	v_div_fmas_f32 v16, v16, v19, v20
	v_div_fixup_f32 v16, v16, v17, 2.0
	v_sub_f32_e32 v16, 1.0, v16
	v_add_f32_e32 v17, 1.0, v18
	v_div_scale_f32 v18, s[22:23], v17, v17, 2.0
	v_rcp_f32_e32 v19, v18
	v_add_f32_e32 v16, 1.0, v16
	v_mul_f32_e32 v1, v1, v16
	ds_write2_b32 v42, v0, v1 offset1:129
	v_fma_f32 v0, -v18, v19, 1.0
	v_fmac_f32_e32 v19, v0, v19
	v_div_scale_f32 v0, vcc, 2.0, v17, 2.0
	v_mul_f32_e32 v1, v0, v19
	v_fma_f32 v16, -v18, v1, v0
	v_fmac_f32_e32 v1, v16, v19
	v_mul_f32_e32 v16, 0x3d372713, v3
	v_mul_f32_e32 v16, v3, v16
	v_fma_f32 v16, v3, v16, v3
	v_mul_f32_e32 v16, 0x3f4c422a, v16
	v_add_f32_e32 v16, v16, v16
	v_mul_f32_e32 v16, 0x3fb8aa3b, v16
	v_exp_f32_e32 v16, v16
	v_fma_f32 v0, -v18, v1, v0
	v_div_fmas_f32 v0, v0, v19, v1
	v_div_fixup_f32 v0, v0, v17, 2.0
	v_add_f32_e32 v1, 1.0, v16
	v_div_scale_f32 v16, s[22:23], v1, v1, 2.0
	v_rcp_f32_e32 v17, v16
	v_sub_f32_e32 v0, 1.0, v0
	v_mul_f32_e32 v2, 0.5, v2
	v_add_f32_e32 v0, 1.0, v0
	v_mul_f32_e32 v0, v2, v0
	v_fma_f32 v2, -v16, v17, 1.0
	v_fmac_f32_e32 v17, v2, v17
	v_div_scale_f32 v2, vcc, 2.0, v1, 2.0
	v_mul_f32_e32 v18, v2, v17
	v_fma_f32 v19, -v16, v18, v2
	v_fmac_f32_e32 v18, v19, v17
	v_fma_f32 v2, -v16, v18, v2
	v_div_fmas_f32 v2, v2, v17, v18
	v_div_fixup_f32 v1, v2, v1, 2.0
	v_mul_f32_e32 v2, 0x3d372713, v4
	v_mul_f32_e32 v2, v4, v2
	v_fma_f32 v2, v4, v2, v4
	v_mul_f32_e32 v2, 0x3f4c422a, v2
	v_add_f32_e32 v2, v2, v2
	v_mul_f32_e32 v2, 0x3fb8aa3b, v2
	v_exp_f32_e32 v2, v2
	v_sub_f32_e32 v1, 1.0, v1
	v_mul_f32_e32 v3, 0.5, v3
	v_add_f32_e32 v1, 1.0, v1
	v_add_f32_e32 v2, 1.0, v2
	v_div_scale_f32 v16, s[22:23], v2, v2, 2.0
	v_rcp_f32_e32 v17, v16
	v_mul_f32_e32 v1, v3, v1
	v_add_u32_e32 v3, 0x400, v42
	ds_write2_b32 v3, v0, v1 offset0:2 offset1:131
	v_fma_f32 v0, -v16, v17, 1.0
	v_fmac_f32_e32 v17, v0, v17
	v_div_scale_f32 v0, vcc, 2.0, v2, 2.0
	v_mul_f32_e32 v1, v0, v17
	v_fma_f32 v3, -v16, v1, v0
	v_fmac_f32_e32 v1, v3, v17
	v_mul_f32_e32 v3, 0x3d372713, v5
	v_mul_f32_e32 v3, v5, v3
	v_fma_f32 v3, v5, v3, v5
	v_mul_f32_e32 v3, 0x3f4c422a, v3
	v_add_f32_e32 v3, v3, v3
	v_mul_f32_e32 v3, 0x3fb8aa3b, v3
	v_exp_f32_e32 v3, v3
	v_fma_f32 v0, -v16, v1, v0
	v_div_fmas_f32 v0, v0, v17, v1
	v_div_fixup_f32 v0, v0, v2, 2.0
	v_add_f32_e32 v1, 1.0, v3
	v_div_scale_f32 v2, s[22:23], v1, v1, 2.0
	v_rcp_f32_e32 v3, v2
	v_sub_f32_e32 v0, 1.0, v0
	v_mul_f32_e32 v4, 0.5, v4
	v_add_f32_e32 v0, 1.0, v0
	v_mul_f32_e32 v0, v4, v0
	v_fma_f32 v4, -v2, v3, 1.0
	v_fmac_f32_e32 v3, v4, v3
	v_div_scale_f32 v4, vcc, 2.0, v1, 2.0
	v_mul_f32_e32 v16, v4, v3
	v_fma_f32 v17, -v2, v16, v4
	v_fmac_f32_e32 v16, v17, v3
	v_fma_f32 v2, -v2, v16, v4
	v_div_fmas_f32 v2, v2, v3, v16
	v_div_fixup_f32 v1, v2, v1, 2.0
	v_mul_f32_e32 v2, 0x3d372713, v6
	v_mul_f32_e32 v2, v6, v2
	v_fma_f32 v2, v6, v2, v6
	v_mul_f32_e32 v2, 0x3f4c422a, v2
	v_add_f32_e32 v2, v2, v2
	v_mul_f32_e32 v2, 0x3fb8aa3b, v2
	v_exp_f32_e32 v2, v2
	v_mul_f32_e32 v3, 0.5, v5
	v_sub_f32_e32 v1, 1.0, v1
	v_add_f32_e32 v1, 1.0, v1
	v_add_f32_e32 v2, 1.0, v2
	v_div_scale_f32 v4, s[22:23], v2, v2, 2.0
	v_rcp_f32_e32 v5, v4
	v_mul_f32_e32 v1, v3, v1
	v_add_u32_e32 v3, 0x1000, v42
	ds_write2_b32 v3, v0, v1 offset0:8 offset1:137
	v_fma_f32 v0, -v4, v5, 1.0
	v_fmac_f32_e32 v5, v0, v5
	v_div_scale_f32 v0, vcc, 2.0, v2, 2.0
	v_mul_f32_e32 v1, v0, v5
	v_fma_f32 v3, -v4, v1, v0
	v_fmac_f32_e32 v1, v3, v5
	v_mul_f32_e32 v3, 0x3d372713, v7
	v_mul_f32_e32 v3, v7, v3
	v_fma_f32 v3, v7, v3, v7
	v_mul_f32_e32 v3, 0x3f4c422a, v3
	v_add_f32_e32 v3, v3, v3
	v_mul_f32_e32 v3, 0x3fb8aa3b, v3
	v_exp_f32_e32 v3, v3
	v_fma_f32 v0, -v4, v1, v0
	v_div_fmas_f32 v0, v0, v5, v1
	v_div_fixup_f32 v0, v0, v2, 2.0
	v_add_f32_e32 v1, 1.0, v3
	v_div_scale_f32 v2, s[22:23], v1, v1, 2.0
	v_rcp_f32_e32 v3, v2
	v_sub_f32_e32 v0, 1.0, v0
	v_mul_f32_e32 v4, 0.5, v6
	v_add_f32_e32 v0, 1.0, v0
	v_mul_f32_e32 v0, v4, v0
	v_fma_f32 v4, -v2, v3, 1.0
	v_fmac_f32_e32 v3, v4, v3
	v_div_scale_f32 v4, vcc, 2.0, v1, 2.0
	v_mul_f32_e32 v5, v4, v3
	v_fma_f32 v6, -v2, v5, v4
	v_fmac_f32_e32 v5, v6, v3
; DI int crow(int r, int hi) { return (r & 3) + 8 * (r >> 2) + 4 * hi; }
; DI float gelu_tanh(float x) {
;     const float y = 0.7978845608028654f * (x + 0.044715f * x * x * x);
;     const float t = __expf(2.f * y);
;     const float th = 1.f - 2.f / (t + 1.f);
;     return 0.5f * x * (1.f + th);
; }
; DI void phase_prep(const Args& a, int layer, LAS unsigned char* lds) {
;     ...
;             for (int r = 0; r < 16; ++r) H[(rg * 32 + crow(r, hi)) * 129 + nt * 32 + c] = gelu_tanh(acc[r]);
;             __syncthreads();
	v_fma_f32 v2, -v2, v5, v4
	v_div_fmas_f32 v2, v2, v3, v5
	v_div_fixup_f32 v1, v2, v1, 2.0
	v_mul_f32_e32 v2, 0x3d372713, v8
	v_mul_f32_e32 v2, v8, v2
	v_fma_f32 v2, v8, v2, v8
	v_mul_f32_e32 v2, 0x3f4c422a, v2
	v_add_f32_e32 v2, v2, v2
	v_mul_f32_e32 v2, 0x3fb8aa3b, v2
	v_exp_f32_e32 v2, v2
	v_sub_f32_e32 v1, 1.0, v1
	v_mul_f32_e32 v3, 0.5, v7
	v_add_f32_e32 v1, 1.0, v1
	v_add_f32_e32 v2, 1.0, v2
	v_div_scale_f32 v4, s[22:23], v2, v2, 2.0
	v_rcp_f32_e32 v5, v4
	v_mul_f32_e32 v1, v3, v1
	v_add_u32_e32 v3, 0x1400, v42
	ds_write2_b32 v3, v0, v1 offset0:10 offset1:139
	v_fma_f32 v0, -v4, v5, 1.0
	v_fmac_f32_e32 v5, v0, v5
	v_div_scale_f32 v0, vcc, 2.0, v2, 2.0
	v_mul_f32_e32 v1, v0, v5
	v_fma_f32 v3, -v4, v1, v0
	v_fmac_f32_e32 v1, v3, v5
	v_mul_f32_e32 v3, 0x3d372713, v9
	v_mul_f32_e32 v3, v9, v3
	v_fma_f32 v3, v9, v3, v9
	v_mul_f32_e32 v3, 0x3f4c422a, v3
	v_add_f32_e32 v3, v3, v3
	v_mul_f32_e32 v3, 0x3fb8aa3b, v3
	v_exp_f32_e32 v3, v3
	v_fma_f32 v0, -v4, v1, v0
	v_div_fmas_f32 v0, v0, v5, v1
	v_div_fixup_f32 v0, v0, v2, 2.0
	v_add_f32_e32 v1, 1.0, v3
	v_div_scale_f32 v2, s[22:23], v1, v1, 2.0
	v_rcp_f32_e32 v3, v2
	v_sub_f32_e32 v0, 1.0, v0
	v_mul_f32_e32 v4, 0.5, v8
	v_add_f32_e32 v0, 1.0, v0
	v_mul_f32_e32 v0, v4, v0
	v_fma_f32 v4, -v2, v3, 1.0
	v_fmac_f32_e32 v3, v4, v3
	v_div_scale_f32 v4, vcc, 2.0, v1, 2.0
	v_mul_f32_e32 v5, v4, v3
	v_fma_f32 v6, -v2, v5, v4
	v_fmac_f32_e32 v5, v6, v3
	v_fma_f32 v2, -v2, v5, v4
	v_div_fmas_f32 v2, v2, v3, v5
	v_div_fixup_f32 v1, v2, v1, 2.0
	v_mul_f32_e32 v2, 0x3d372713, v10
	v_mul_f32_e32 v2, v10, v2
	v_fma_f32 v2, v10, v2, v10
	v_mul_f32_e32 v2, 0x3f4c422a, v2
	v_add_f32_e32 v2, v2, v2
	v_mul_f32_e32 v2, 0x3fb8aa3b, v2
	v_exp_f32_e32 v2, v2
	v_sub_f32_e32 v1, 1.0, v1
	v_mul_f32_e32 v3, 0.5, v9
	v_add_f32_e32 v1, 1.0, v1
	v_add_f32_e32 v2, 1.0, v2
	v_div_scale_f32 v4, s[22:23], v2, v2, 2.0
	v_rcp_f32_e32 v5, v4
	v_mul_f32_e32 v1, v3, v1
	v_add_u32_e32 v3, 0x2000, v42
	ds_write2_b32 v3, v0, v1 offset0:16 offset1:145
	v_fma_f32 v0, -v4, v5, 1.0
	v_fmac_f32_e32 v5, v0, v5
	v_div_scale_f32 v0, vcc, 2.0, v2, 2.0
	v_mul_f32_e32 v1, v0, v5
	v_fma_f32 v3, -v4, v1, v0
	v_fmac_f32_e32 v1, v3, v5
	v_mul_f32_e32 v3, 0x3d372713, v11
	v_mul_f32_e32 v3, v11, v3
	v_fma_f32 v3, v11, v3, v11
	v_mul_f32_e32 v3, 0x3f4c422a, v3
	v_add_f32_e32 v3, v3, v3
	v_mul_f32_e32 v3, 0x3fb8aa3b, v3
	v_exp_f32_e32 v3, v3
	v_fma_f32 v0, -v4, v1, v0
	v_div_fmas_f32 v0, v0, v5, v1
	v_div_fixup_f32 v0, v0, v2, 2.0
	v_add_f32_e32 v1, 1.0, v3
	v_div_scale_f32 v2, s[22:23], v1, v1, 2.0
	v_rcp_f32_e32 v3, v2
	v_sub_f32_e32 v0, 1.0, v0
	v_mul_f32_e32 v4, 0.5, v10
	v_add_f32_e32 v0, 1.0, v0
	v_mul_f32_e32 v0, v4, v0
	v_fma_f32 v4, -v2, v3, 1.0
	v_fmac_f32_e32 v3, v4, v3
	v_div_scale_f32 v4, vcc, 2.0, v1, 2.0
	v_mul_f32_e32 v5, v4, v3
	v_fma_f32 v6, -v2, v5, v4
	v_fmac_f32_e32 v5, v6, v3
	v_fma_f32 v2, -v2, v5, v4
	v_div_fmas_f32 v2, v2, v3, v5
	v_div_fixup_f32 v1, v2, v1, 2.0
	v_mul_f32_e32 v2, 0x3d372713, v12
	v_mul_f32_e32 v2, v12, v2
	v_fma_f32 v2, v12, v2, v12
	v_mul_f32_e32 v2, 0x3f4c422a, v2
	v_add_f32_e32 v2, v2, v2
	v_mul_f32_e32 v2, 0x3fb8aa3b, v2
	v_exp_f32_e32 v2, v2
	v_sub_f32_e32 v1, 1.0, v1
	v_mul_f32_e32 v3, 0.5, v11
	v_add_f32_e32 v1, 1.0, v1
	v_add_f32_e32 v2, 1.0, v2
	v_div_scale_f32 v4, s[22:23], v2, v2, 2.0
	v_rcp_f32_e32 v5, v4
	v_mul_f32_e32 v1, v3, v1
	v_add_u32_e32 v3, 0x2400, v42
	ds_write2_b32 v3, v0, v1 offset0:18 offset1:147
	v_fma_f32 v0, -v4, v5, 1.0
	v_fmac_f32_e32 v5, v0, v5
	v_div_scale_f32 v0, vcc, 2.0, v2, 2.0
	v_mul_f32_e32 v1, v0, v5
	v_fma_f32 v3, -v4, v1, v0
	v_fmac_f32_e32 v1, v3, v5
	v_mul_f32_e32 v3, 0x3d372713, v13
	v_mul_f32_e32 v3, v13, v3
	v_fma_f32 v3, v13, v3, v13
	v_mul_f32_e32 v3, 0x3f4c422a, v3
	v_add_f32_e32 v3, v3, v3
	v_mul_f32_e32 v3, 0x3fb8aa3b, v3
	v_exp_f32_e32 v3, v3
	v_fma_f32 v0, -v4, v1, v0
	v_div_fmas_f32 v0, v0, v5, v1
	v_div_fixup_f32 v0, v0, v2, 2.0
	v_add_f32_e32 v1, 1.0, v3
	v_div_scale_f32 v2, s[22:23], v1, v1, 2.0
	v_rcp_f32_e32 v3, v2
	v_sub_f32_e32 v0, 1.0, v0
	v_mul_f32_e32 v4, 0.5, v12
	v_add_f32_e32 v0, 1.0, v0
	v_mul_f32_e32 v0, v4, v0
	v_fma_f32 v4, -v2, v3, 1.0
	v_fmac_f32_e32 v3, v4, v3
	v_div_scale_f32 v4, vcc, 2.0, v1, 2.0
	v_mul_f32_e32 v5, v4, v3
	v_fma_f32 v6, -v2, v5, v4
	v_fmac_f32_e32 v5, v6, v3
	v_fma_f32 v2, -v2, v5, v4
	v_div_fmas_f32 v2, v2, v3, v5
	v_div_fixup_f32 v1, v2, v1, 2.0
	v_mul_f32_e32 v2, 0x3d372713, v14
	v_mul_f32_e32 v2, v14, v2
	v_fma_f32 v2, v14, v2, v14
	v_mul_f32_e32 v2, 0x3f4c422a, v2
	v_add_f32_e32 v2, v2, v2
	v_mul_f32_e32 v2, 0x3fb8aa3b, v2
	v_exp_f32_e32 v2, v2
	v_sub_f32_e32 v1, 1.0, v1
	v_mul_f32_e32 v3, 0.5, v13
	v_add_f32_e32 v1, 1.0, v1
	v_add_f32_e32 v2, 1.0, v2
	v_div_scale_f32 v4, s[22:23], v2, v2, 2.0
	v_rcp_f32_e32 v5, v4
	v_mul_f32_e32 v1, v3, v1
	v_add_u32_e32 v3, 0x3000, v42
	ds_write2_b32 v3, v0, v1 offset0:24 offset1:153
	v_fma_f32 v0, -v4, v5, 1.0
	v_fmac_f32_e32 v5, v0, v5
	v_div_scale_f32 v0, vcc, 2.0, v2, 2.0
	v_mul_f32_e32 v1, v0, v5
	v_fma_f32 v3, -v4, v1, v0
	v_fmac_f32_e32 v1, v3, v5
	v_mul_f32_e32 v3, 0x3d372713, v15
	v_mul_f32_e32 v3, v15, v3
	v_fma_f32 v3, v15, v3, v15
	v_mul_f32_e32 v3, 0x3f4c422a, v3
	v_add_f32_e32 v3, v3, v3
	v_mul_f32_e32 v3, 0x3fb8aa3b, v3
	v_exp_f32_e32 v3, v3
	v_fma_f32 v0, -v4, v1, v0
	v_div_fmas_f32 v0, v0, v5, v1
	v_div_fixup_f32 v0, v0, v2, 2.0
	v_add_f32_e32 v1, 1.0, v3
	v_div_scale_f32 v2, s[22:23], v1, v1, 2.0
	v_rcp_f32_e32 v3, v2
	v_sub_f32_e32 v0, 1.0, v0
	v_mul_f32_e32 v4, 0.5, v14
	v_add_f32_e32 v0, 1.0, v0
	v_mul_f32_e32 v0, v4, v0
	v_fma_f32 v4, -v2, v3, 1.0
	v_fmac_f32_e32 v3, v4, v3
	v_div_scale_f32 v4, vcc, 2.0, v1, 2.0
	v_mul_f32_e32 v5, v4, v3
	v_fma_f32 v6, -v2, v5, v4
	v_fmac_f32_e32 v5, v6, v3
	v_fma_f32 v2, -v2, v5, v4
	v_div_fmas_f32 v2, v2, v3, v5
	v_div_fixup_f32 v1, v2, v1, 2.0
	v_sub_f32_e32 v1, 1.0, v1
	v_mul_f32_e32 v2, 0.5, v15
	v_add_f32_e32 v1, 1.0, v1
	s_add_u32 s22, s9, s24
	v_mul_f32_e32 v1, v2, v1
	v_add_u32_e32 v2, 0x3400, v42
	s_addc_u32 s23, s8, s25
	v_mov_b32_e32 v29, v129
	v_mov_b32_e32 v4, 0
	ds_write2_b32 v2, v0, v1 offset0:26 offset1:155
	v_lshl_add_u64 v[0:1], s[22:23], 0, v[28:29]
	s_mov_b64 s[8:9], 0
	v_mov_b32_e32 v12, v44
	v_mov_b32_e32 v5, v4
	v_mov_b32_e32 v6, v4
	v_mov_b32_e32 v7, v4
	v_mov_b32_e32 v10, v4
	v_mov_b32_e32 v11, v4
	v_mov_b32_e32 v8, v4
	v_mov_b32_e32 v9, v4
	s_waitcnt lgkmcnt(0)
	s_barrier
; DI void phase_prep(const Args& a, int layer, LAS unsigned char* lds) {
;     ...
;             {
;                 const int i = tid >> 3, dc = (tid & 7) * 8;
;                 float o[8];
; #pragma unroll
;                 for (int e = 0; e < 8; ++e) o[e] = 0.f;
;                 for (int n = 0; n < 128; ++n) {
;                     const float hv = H[i * 129 + n];
;                     const f32x4 wa = *(const f32x4*)(w2 + n * 64 + dc), wb = *(const f32x4*)(w2 + n * 64 + dc + 4);
;                     o[0] += hv * wa.x; o[1] += hv * wa.y; o[2] += hv * wa.z; o[3] += hv * wa.w;
;                     o[4] += hv * wb.x; o[5] += hv * wb.y; o[6] += hv * wb.z; o[7] += hv * wb.w;
;                 }
;                 const int ig = rt * 64 + i;
;                 if (ig > 1022) {
; #pragma unroll
;                     for (int e = 0; e < 8; ++e) o[e] = 0.f;
;                 }
;                 if (kv == 0) {
;                     u32x4 w; w.x = pk2(o[0], o[1]); w.y = pk2(o[2], o[3]); w.z = pk2(o[4], o[5]); w.w = pk2(o[6], o[7]);
;                     float ss = bflo(w.x) * bflo(w.x) + bfhi(w.x) * bfhi(w.x) + bflo(w.y) * bflo(w.y) + bfhi(w.y) * bfhi(w.y)
;                              + bflo(w.z) * bflo(w.z) + bfhi(w.z) * bfhi(w.z) + bflo(w.w) * bflo(w.w) + bfhi(w.w) * bfhi(w.w);
;                     ss += __shfl_xor(ss, 1); ss += __shfl_xor(ss, 2); ss += __shfl_xor(ss, 4);
;                     ss = fmaxf(ss, __shfl_xor(ss, 8)); ss = fmaxf(ss, __shfl_xor(ss, 16)); ss = fmaxf(ss, __shfl_xor(ss, 32));
;                     if (lane == 0) atomicMax((unsigned*)(ws + WS_KMAX) + (layer * 4 + 3) * 4 + bg, __builtin_bit_cast(unsigned, ss));
;                     const int q = dc >> 3;
;                     *(u32x4*)((bf16_t*)(ws + WS_KC) + (size_t)bg * NCP * 64 + (size_t)(ig >> 5) * 2048 + ((q >> 1) * 64 + (q & 1) * 32 + (ig & 31)) * 8) = w;
;                 } else {
;                     const int kk5 = ig & 31, jj = kk5 >> 4, rem = kk5 & 15, hh1 = (rem >> 2) & 1, ii = (rem >> 3) * 4 + (rem & 3);
;                     bf16_t* vt = (bf16_t*)(ws + WS_VCT) + (size_t)bg * 64 * NCP + (size_t)(ig >> 5) * 2048 + ii;
; #pragma unroll
;                     for (int e = 0; e < 8; ++e) { const int dd = dc + e; vt[((jj * 2 + (dd >> 5)) * 64 + hh1 * 32 + (dd & 31)) * 8] = (bf16_t)f2bf(o[e]); }
.LBB0_397:
	s_waitcnt vmcnt(0)
	global_load_dwordx4 v[48:51], v[0:1], off
	global_load_dwordx4 v[52:55], v[0:1], off offset:16
	global_load_dwordx4 v[56:59], v[0:1], off offset:256
	global_load_dwordx4 v[60:63], v[0:1], off offset:272
	global_load_dwordx4 v[64:67], v[0:1], off offset:512
	global_load_dwordx4 v[68:71], v[0:1], off offset:528
	global_load_dwordx4 v[72:75], v[0:1], off offset:768
	global_load_dwordx4 v[76:79], v[0:1], off offset:784
	global_load_dwordx4 v[80:83], v[0:1], off offset:1024
	global_load_dwordx4 v[84:87], v[0:1], off offset:1040
	global_load_dwordx4 v[88:91], v[0:1], off offset:1280
	global_load_dwordx4 v[92:95], v[0:1], off offset:1296
	global_load_dwordx4 v[96:99], v[0:1], off offset:1536
	global_load_dwordx4 v[100:103], v[0:1], off offset:1552
	global_load_dwordx4 v[104:107], v[0:1], off offset:1792
	global_load_dwordx4 v[108:111], v[0:1], off offset:1808
	v_mov_b32_e32 v13, v12
	s_movk_i32 s8, 0x800
	s_mov_b32 s17, 0
.Lp_w2_loop:
	s_cmpk_eq_u32 s8, 0x8000
	s_cselect_b32 s16, 0, s8
	v_lshl_add_u64 v[2:3], v[0:1], 0, s[16:17]
	ds_read2_b32 v[22:23], v13 offset0:0 offset1:1
	s_waitcnt vmcnt(14) lgkmcnt(0)
	v_pk_fma_f32 v[4:5], v[22:23], v[48:49], v[4:5] op_sel_hi:[0,1,1]
	v_pk_fma_f32 v[6:7], v[22:23], v[50:51], v[6:7] op_sel_hi:[0,1,1]
	v_pk_fma_f32 v[10:11], v[22:23], v[52:53], v[10:11] op_sel_hi:[0,1,1]
	v_pk_fma_f32 v[8:9], v[22:23], v[54:55], v[8:9] op_sel_hi:[0,1,1]
	global_load_dwordx4 v[48:51], v[2:3], off
	global_load_dwordx4 v[52:55], v[2:3], off offset:16
	s_waitcnt vmcnt(14)
	v_pk_fma_f32 v[4:5], v[22:23], v[56:57], v[4:5] op_sel:[1,0,0]
	v_pk_fma_f32 v[6:7], v[22:23], v[58:59], v[6:7] op_sel:[1,0,0]
	v_pk_fma_f32 v[10:11], v[22:23], v[60:61], v[10:11] op_sel:[1,0,0]
	v_pk_fma_f32 v[8:9], v[22:23], v[62:63], v[8:9] op_sel:[1,0,0]
	global_load_dwordx4 v[56:59], v[2:3], off offset:256
	global_load_dwordx4 v[60:63], v[2:3], off offset:272
	ds_read2_b32 v[22:23], v13 offset0:2 offset1:3
	s_waitcnt vmcnt(14) lgkmcnt(0)
	v_pk_fma_f32 v[4:5], v[22:23], v[64:65], v[4:5] op_sel_hi:[0,1,1]
	v_pk_fma_f32 v[6:7], v[22:23], v[66:67], v[6:7] op_sel_hi:[0,1,1]
	v_pk_fma_f32 v[10:11], v[22:23], v[68:69], v[10:11] op_sel_hi:[0,1,1]
	v_pk_fma_f32 v[8:9], v[22:23], v[70:71], v[8:9] op_sel_hi:[0,1,1]
	global_load_dwordx4 v[64:67], v[2:3], off offset:512
	global_load_dwordx4 v[68:71], v[2:3], off offset:528
	s_waitcnt vmcnt(14)
	v_pk_fma_f32 v[4:5], v[22:23], v[72:73], v[4:5] op_sel:[1,0,0]
	v_pk_fma_f32 v[6:7], v[22:23], v[74:75], v[6:7] op_sel:[1,0,0]
	v_pk_fma_f32 v[10:11], v[22:23], v[76:77], v[10:11] op_sel:[1,0,0]
	v_pk_fma_f32 v[8:9], v[22:23], v[78:79], v[8:9] op_sel:[1,0,0]
	global_load_dwordx4 v[72:75], v[2:3], off offset:768
	global_load_dwordx4 v[76:79], v[2:3], off offset:784
	ds_read2_b32 v[22:23], v13 offset0:4 offset1:5
	s_waitcnt vmcnt(14) lgkmcnt(0)
	v_pk_fma_f32 v[4:5], v[22:23], v[80:81], v[4:5] op_sel_hi:[0,1,1]
	v_pk_fma_f32 v[6:7], v[22:23], v[82:83], v[6:7] op_sel_hi:[0,1,1]
	v_pk_fma_f32 v[10:11], v[22:23], v[84:85], v[10:11] op_sel_hi:[0,1,1]
	v_pk_fma_f32 v[8:9], v[22:23], v[86:87], v[8:9] op_sel_hi:[0,1,1]
	global_load_dwordx4 v[80:83], v[2:3], off offset:1024
	global_load_dwordx4 v[84:87], v[2:3], off offset:1040
	s_waitcnt vmcnt(14)
	v_pk_fma_f32 v[4:5], v[22:23], v[88:89], v[4:5] op_sel:[1,0,0]
	v_pk_fma_f32 v[6:7], v[22:23], v[90:91], v[6:7] op_sel:[1,0,0]
	v_pk_fma_f32 v[10:11], v[22:23], v[92:93], v[10:11] op_sel:[1,0,0]
	v_pk_fma_f32 v[8:9], v[22:23], v[94:95], v[8:9] op_sel:[1,0,0]
	global_load_dwordx4 v[88:91], v[2:3], off offset:1280
	global_load_dwordx4 v[92:95], v[2:3], off offset:1296
	ds_read2_b32 v[22:23], v13 offset0:6 offset1:7
	s_waitcnt vmcnt(14) lgkmcnt(0)
	v_pk_fma_f32 v[4:5], v[22:23], v[96:97], v[4:5] op_sel_hi:[0,1,1]
	v_pk_fma_f32 v[6:7], v[22:23], v[98:99], v[6:7] op_sel_hi:[0,1,1]
	v_pk_fma_f32 v[10:11], v[22:23], v[100:101], v[10:11] op_sel_hi:[0,1,1]
	v_pk_fma_f32 v[8:9], v[22:23], v[102:103], v[8:9] op_sel_hi:[0,1,1]
	global_load_dwordx4 v[96:99], v[2:3], off offset:1536
	global_load_dwordx4 v[100:103], v[2:3], off offset:1552
	s_waitcnt vmcnt(14)
	v_pk_fma_f32 v[4:5], v[22:23], v[104:105], v[4:5] op_sel:[1,0,0]
	v_pk_fma_f32 v[6:7], v[22:23], v[106:107], v[6:7] op_sel:[1,0,0]
	v_pk_fma_f32 v[10:11], v[22:23], v[108:109], v[10:11] op_sel:[1,0,0]
	v_pk_fma_f32 v[8:9], v[22:23], v[110:111], v[8:9] op_sel:[1,0,0]
	global_load_dwordx4 v[104:107], v[2:3], off offset:1792
	global_load_dwordx4 v[108:111], v[2:3], off offset:1808
	v_add_u32_e32 v13, 32, v13
	s_addk_i32 s8, 0x800
	s_cmpk_lg_u32 s8, 0x8800
	s_cbranch_scc1 .Lp_w2_loop
	s_waitcnt vmcnt(0)
	s_lshl_b32 s8, s35, 6
	s_and_b32 s8, s8, 0x3c0
	v_add_u32_e32 v12, s8, v46
	v_cmp_gt_i32_e32 vcc, s5, v12
	s_and_b32 s16, s48, 3
	s_mov_b64 s[8:9], -1
	v_cndmask_b32_e32 v1, 0, v7, vcc
	v_cndmask_b32_e32 v7, 0, v4, vcc
	v_ashrrev_i32_e32 v4, 5, v12
	v_cndmask_b32_e32 v3, 0, v9, vcc
	v_cndmask_b32_e32 v8, 0, v8, vcc
	v_cndmask_b32_e32 v2, 0, v11, vcc
	v_cndmask_b32_e32 v9, 0, v10, vcc
	v_cndmask_b32_e32 v6, 0, v6, vcc
	v_cndmask_b32_e32 v0, 0, v5, vcc
	s_and_b64 vcc, exec, s[42:43]
	v_ashrrev_i32_e32 v5, 31, v4
	s_cbranch_vccz .LBB0_400
	s_lshl_b32 s8, s16, 17
	v_readlane_b32 s9, v252, 37
	s_add_u32 s8, s9, s8
	v_readlane_b32 s9, v252, 38
	s_addc_u32 s9, s9, 0
	v_lshlrev_b64 v[10:11], 12, v[4:5]
	v_lshl_add_u64 v[10:11], s[8:9], 0, v[10:11]
	v_mov_b32_e32 v31, v129
	v_lshl_add_u64 v[10:11], v[10:11], 0, v[30:31]
	v_bfe_u32 v12, v7, 16, 1
	v_mov_b32_e32 v33, v129
	v_add3_u32 v12, v7, v12, s28
	v_lshl_add_u64 v[10:11], v[10:11], 0, v[32:33]
	global_store_short_d16_hi v[10:11], v12, off
	v_bfe_u32 v12, v0, 16, 1
	v_add3_u32 v12, v0, v12, s28
	global_store_short_d16_hi v[10:11], v12, off offset:16
	v_bfe_u32 v12, v6, 16, 1
	v_add3_u32 v12, v6, v12, s28
	global_store_short_d16_hi v[10:11], v12, off offset:32
	v_bfe_u32 v12, v1, 16, 1
	v_add3_u32 v12, v1, v12, s28
	global_store_short_d16_hi v[10:11], v12, off offset:48
	v_bfe_u32 v12, v9, 16, 1
	v_add3_u32 v12, v9, v12, s28
	global_store_short_d16_hi v[10:11], v12, off offset:64
	v_bfe_u32 v12, v2, 16, 1
	v_add3_u32 v12, v2, v12, s28
	global_store_short_d16_hi v[10:11], v12, off offset:80
	v_bfe_u32 v12, v8, 16, 1
	v_add3_u32 v12, v8, v12, s28
	global_store_short_d16_hi v[10:11], v12, off offset:96
	v_bfe_u32 v12, v3, 16, 1
	v_add3_u32 v12, v3, v12, s28
	global_store_short_d16_hi v[10:11], v12, off offset:112
	s_mov_b64 s[8:9], 0
